# P4 softmax epilogue: cross-row max/sum reductions via v_permlane16_swap/v_permlane32_swap (copy, swap, combine) instead of 32 serialized ds_bpermute round trips per unit; on top of the v36 stack
# speedup vs baseline: 1.0009x; 1.0009x over previous
; __device__ __forceinline__ float row_rstd(const float* slots, int row) {
;     const f32x4* s = (const f32x4*)(slots + (size_t)row * 16);
;     const f32x4 a = s[0], b = s[1], c = s[2], d = s[3];
;     const f32x4 t = (a + b) + (c + d);
;     const float ss = (t[0] + t[1]) + (t[2] + t[3]);
;     return __builtin_amdgcn_rsqf(ss * (1.0f / 1024.0f) + 1e-6f);
;     __device__ __forceinline__ void operator()(f32x4 (&acc)[2][2][4][2], const Unit& u, int wr, int wc, int fr, int fq) const {
;     ...
;         for (int ai = 0; ai < 2; ++ai) loc[ai] = scale * row_rstd(slots, u.pm * BM + wr * 64 + ai * HALF + fq * 16 + fr);
; #pragma unroll
;         for (int ai = 0; ai < 2; ++ai)
; #pragma unroll
;             for (int m = 0; m < 4; ++m) { float mx = -3.0e38f; const float rsm = __shfl(loc[ai], m * 16 + fr);
; #pragma unroll
;                 for (int bj = 0; bj < 2; ++bj)
; #pragma unroll
;                     for (int n = 0; n < 2; ++n) { const f32x4 x = acc[ai][bj][m][n] * rsm; acc[ai][bj][m][n] = x; mx = fmaxf(fmaxf(mx, fmaxf(x[0], x[1])), fmaxf(x[2], x[3])); }
;                 mx = fmaxf(mx, __shfl_xor(mx, 16)); mx = fmaxf(mx, __shfl_xor(mx, 32));
;                 if (fq == 0) xch[(ai * HALF + wr * 64 + m * 16 + fr) * 4 + wc] = mx; }
.LBB0_690:
	s_lshl_b32 s13, s67, 8
	v_add_u32_e32 v158, s13, v213
	v_ashrrev_i32_e32 v159, 31, v158
	v_lshlrev_b64 v[128:129], 6, v[158:159]
	v_lshl_add_u64 v[140:141], s[4:5], 0, v[128:129]
	global_load_dwordx4 v[128:131], v[140:141], off
	global_load_dwordx4 v[132:135], v[140:141], off offset:16
	global_load_dwordx4 v[136:139], v[140:141], off offset:32
	s_nop 0
	global_load_dwordx4 v[140:143], v[140:141], off offset:48
	v_and_b32_e32 v157, 64, v252
	v_xor_b32_e32 v159, 16, v252
	s_waitcnt vmcnt(0) lgkmcnt(0)
	v_pk_add_f32 v[130:131], v[130:131], v[134:135]
	v_pk_add_f32 v[128:129], v[128:129], v[132:133]
	v_pk_add_f32 v[132:133], v[138:139], v[142:143]
	v_pk_add_f32 v[134:135], v[136:137], v[140:141]
	v_pk_add_f32 v[130:131], v[130:131], v[132:133]
	v_pk_add_f32 v[128:129], v[128:129], v[134:135]
	s_nop 0
	v_pk_mov_b32 v[132:133], v[128:129], v[130:131] op_sel:[1,0]
	v_mov_b32_e32 v129, v131
	v_pk_add_f32 v[128:129], v[132:133], v[128:129]
	s_nop 0
	v_add_f32_e32 v128, v128, v129
	v_fmamk_f32 v128, v128, 0x3a800000, v244
	v_rsq_f32_e32 v128, v128
	s_nop 0
	v_mul_f32_e32 v156, 0x3db8aa3b, v128
	v_add_u32_e32 v128, 0x80, v158
	v_ashrrev_i32_e32 v129, 31, v128
	v_lshlrev_b64 v[128:129], 6, v[128:129]
	v_lshl_add_u64 v[132:133], s[4:5], 0, v[128:129]
	global_load_dwordx4 v[136:139], v[132:133], off
	global_load_dwordx4 v[140:143], v[132:133], off offset:16
	global_load_dwordx4 v[128:131], v[132:133], off offset:32
	s_nop 0
	global_load_dwordx4 v[132:135], v[132:133], off offset:48
	v_or_b32_e32 v158, v157, v210
	v_lshlrev_b32_e32 v236, 2, v158
	ds_bpermute_b32 v158, v236, v156
	v_add_u32_e32 v157, 64, v157
	v_cmp_lt_i32_e32 vcc, v159, v157
	s_nop 1
	v_cndmask_b32_e32 v159, v252, v159, vcc
	v_lshlrev_b32_e32 v234, 2, v159
	v_xor_b32_e32 v159, 32, v252
	v_cmp_lt_i32_e32 vcc, v159, v157
	s_waitcnt lgkmcnt(0)
	v_pk_mul_f32 v[126:127], v[126:127], v[158:159] op_sel_hi:[1,0]
	v_pk_mul_f32 v[124:125], v[124:125], v[158:159] op_sel_hi:[1,0]
	v_cndmask_b32_e32 v157, v252, v159, vcc
	v_max_f32_e32 v159, v126, v127
	v_lshlrev_b32_e32 v235, 2, v157
	v_max_f32_e32 v157, v124, v125
	v_pk_mul_f32 v[122:123], v[122:123], v[158:159] op_sel_hi:[1,0]
	v_pk_mul_f32 v[180:181], v[120:121], v[158:159] op_sel_hi:[1,0]
	v_max3_f32 v157, v157, s6, v159
	v_max_f32_e32 v120, v180, v181
	v_max_f32_e32 v121, v122, v123
	v_max3_f32 v157, v157, v120, v121
	v_pk_mul_f32 v[120:121], v[118:119], v[158:159] op_sel_hi:[1,0]
	v_pk_mul_f32 v[182:183], v[116:117], v[158:159] op_sel_hi:[1,0]
	v_max_f32_e32 v117, v120, v121
	v_max_f32_e32 v116, v182, v183
	v_pk_mul_f32 v[114:115], v[114:115], v[158:159] op_sel_hi:[1,0]
	v_pk_mul_f32 v[112:113], v[112:113], v[158:159] op_sel_hi:[1,0]
	v_max3_f32 v116, v157, v116, v117
	v_max_f32_e32 v117, v112, v113
	v_max_f32_e32 v118, v114, v115
	v_max3_f32 v116, v116, v117, v118
	v_mov_b32_e32 v117, v116
	s_nop 1
	v_permlane16_swap_b32_e32 v117, v116
	s_waitcnt lgkmcnt(0)
	v_max_f32_e32 v117, v117, v117
	v_max_f32_e32 v116, v116, v117
	v_mov_b32_e32 v117, v116
	s_nop 1
	v_permlane32_swap_b32_e32 v117, v116
	s_and_saveexec_b64 s[22:23], s[40:41]
	s_cbranch_execz .LBB0_692
	s_waitcnt lgkmcnt(0)
	v_max_f32_e32 v117, v117, v117
	v_max_f32_e32 v116, v116, v116
	v_max_f32_e32 v116, v116, v117
	ds_write_b32 v223, v116
.LBB0_692:
	s_or_b64 exec, exec, s[22:23]
	ds_bpermute_b32 v116, v236, v156 offset:64
	s_waitcnt lgkmcnt(0)
	v_pk_mul_f32 v[206:207], v[110:111], v[116:117] op_sel_hi:[1,0]
	v_pk_mul_f32 v[208:209], v[108:109], v[116:117] op_sel_hi:[1,0]
	v_pk_mul_f32 v[200:201], v[106:107], v[116:117] op_sel_hi:[1,0]
	v_pk_mul_f32 v[204:205], v[104:105], v[116:117] op_sel_hi:[1,0]
	v_max_f32_e32 v104, v208, v209
	v_max_f32_e32 v105, v206, v207
	v_max3_f32 v104, v104, s6, v105
	v_max_f32_e32 v105, v204, v205
	v_max_f32_e32 v106, v200, v201
	v_max3_f32 v106, v104, v105, v106
	v_pk_mul_f32 v[104:105], v[102:103], v[116:117] op_sel_hi:[1,0]
	v_pk_mul_f32 v[202:203], v[100:101], v[116:117] op_sel_hi:[1,0]
	v_max_f32_e32 v101, v104, v105
	v_max_f32_e32 v100, v202, v203
	v_pk_mul_f32 v[198:199], v[94:95], v[116:117] op_sel_hi:[1,0]
	v_pk_mul_f32 v[102:103], v[92:93], v[116:117] op_sel_hi:[1,0]
	v_max3_f32 v100, v106, v100, v101
	v_max_f32_e32 v92, v102, v103
	v_max_f32_e32 v93, v198, v199
	v_max3_f32 v92, v100, v92, v93
	v_mov_b32_e32 v93, v92
	s_nop 1
	v_permlane16_swap_b32_e32 v93, v92
	s_waitcnt lgkmcnt(0)
	v_max_f32_e32 v93, v93, v93
	v_max_f32_e32 v92, v92, v93
	v_mov_b32_e32 v93, v92
	s_nop 1
	v_permlane32_swap_b32_e32 v93, v92
	s_and_saveexec_b64 s[22:23], s[40:41]
	s_cbranch_execz .LBB0_694
	s_waitcnt lgkmcnt(0)
	v_max_f32_e32 v93, v93, v93
	v_max_f32_e32 v92, v92, v92
	v_max_f32_e32 v92, v92, v93
	ds_write_b32 v223, v92 offset:256
.LBB0_694:
	s_or_b64 exec, exec, s[22:23]
	ds_bpermute_b32 v92, v236, v156 offset:128
	s_waitcnt lgkmcnt(0)
	v_pk_mul_f32 v[188:189], v[98:99], v[92:93] op_sel_hi:[1,0]
	v_pk_mul_f32 v[190:191], v[96:97], v[92:93] op_sel_hi:[1,0]
	v_pk_mul_f32 v[96:97], v[90:91], v[92:93] op_sel_hi:[1,0]
	v_pk_mul_f32 v[186:187], v[88:89], v[92:93] op_sel_hi:[1,0]
	v_max_f32_e32 v88, v190, v191
	v_max_f32_e32 v89, v188, v189
	v_max3_f32 v88, v88, s6, v89
	v_max_f32_e32 v89, v186, v187
	v_max_f32_e32 v90, v96, v97
	v_max3_f32 v90, v88, v89, v90
	v_pk_mul_f32 v[88:89], v[86:87], v[92:93] op_sel_hi:[1,0]
	v_pk_mul_f32 v[184:185], v[84:85], v[92:93] op_sel_hi:[1,0]
	v_max_f32_e32 v85, v88, v89
	v_max_f32_e32 v84, v184, v185
	v_pk_mul_f32 v[98:99], v[78:79], v[92:93] op_sel_hi:[1,0]
	v_pk_mul_f32 v[86:87], v[76:77], v[92:93] op_sel_hi:[1,0]
	v_max3_f32 v84, v90, v84, v85
	v_max_f32_e32 v76, v86, v87
	v_max_f32_e32 v77, v98, v99
	v_max3_f32 v76, v84, v76, v77
	v_mov_b32_e32 v77, v76
	s_nop 1
	v_permlane16_swap_b32_e32 v77, v76
	s_waitcnt lgkmcnt(0)
	v_max_f32_e32 v77, v77, v77
	v_max_f32_e32 v76, v76, v77
	v_mov_b32_e32 v77, v76
	s_nop 1
	v_permlane32_swap_b32_e32 v77, v76
	s_and_saveexec_b64 s[22:23], s[40:41]
	s_cbranch_execz .LBB0_696
	s_waitcnt lgkmcnt(0)
	v_max_f32_e32 v77, v77, v77
	v_max_f32_e32 v76, v76, v76
	v_max_f32_e32 v76, v76, v77
	ds_write_b32 v223, v76 offset:512
; __device__ __forceinline__ float row_rstd(const float* slots, int row) {
;     const f32x4* s = (const f32x4*)(slots + (size_t)row * 16);
;     const f32x4 a = s[0], b = s[1], c = s[2], d = s[3];
;     const f32x4 t = (a + b) + (c + d);
;     const float ss = (t[0] + t[1]) + (t[2] + t[3]);
;     return __builtin_amdgcn_rsqf(ss * (1.0f / 1024.0f) + 1e-6f);
;     __device__ __forceinline__ void operator()(f32x4 (&acc)[2][2][4][2], const Unit& u, int wr, int wc, int fr, int fq) const {
;     ...
;         for (int ai = 0; ai < 2; ++ai) loc[ai] = scale * row_rstd(slots, u.pm * BM + wr * 64 + ai * HALF + fq * 16 + fr);
; #pragma unroll
;         for (int ai = 0; ai < 2; ++ai)
; #pragma unroll
;             for (int m = 0; m < 4; ++m) { float mx = -3.0e38f; const float rsm = __shfl(loc[ai], m * 16 + fr);
; #pragma unroll
;                 for (int bj = 0; bj < 2; ++bj)
; #pragma unroll
;                     for (int n = 0; n < 2; ++n) { const f32x4 x = acc[ai][bj][m][n] * rsm; acc[ai][bj][m][n] = x; mx = fmaxf(fmaxf(mx, fmaxf(x[0], x[1])), fmaxf(x[2], x[3])); }
;                 mx = fmaxf(mx, __shfl_xor(mx, 16)); mx = fmaxf(mx, __shfl_xor(mx, 32));
;                 if (fq == 0) xch[(ai * HALF + wr * 64 + m * 16 + fr) * 4 + wc] = mx; }
.LBB0_696:
	s_or_b64 exec, exec, s[22:23]
	ds_bpermute_b32 v76, v236, v156 offset:192
	s_waitcnt lgkmcnt(0)
	v_pk_mul_f32 v[176:177], v[82:83], v[76:77] op_sel_hi:[1,0]
	v_pk_mul_f32 v[178:179], v[80:81], v[76:77] op_sel_hi:[1,0]
	v_pk_mul_f32 v[80:81], v[74:75], v[76:77] op_sel_hi:[1,0]
	v_pk_mul_f32 v[174:175], v[72:73], v[76:77] op_sel_hi:[1,0]
	v_max_f32_e32 v72, v178, v179
	v_max_f32_e32 v73, v176, v177
	v_max3_f32 v72, v72, s6, v73
	v_max_f32_e32 v73, v174, v175
	v_max_f32_e32 v74, v80, v81
	v_max3_f32 v74, v72, v73, v74
	v_pk_mul_f32 v[72:73], v[70:71], v[76:77] op_sel_hi:[1,0]
	v_pk_mul_f32 v[170:171], v[68:69], v[76:77] op_sel_hi:[1,0]
	v_max_f32_e32 v69, v72, v73
	v_max_f32_e32 v68, v170, v171
	v_pk_mul_f32 v[82:83], v[66:67], v[76:77] op_sel_hi:[1,0]
	v_pk_mul_f32 v[70:71], v[64:65], v[76:77] op_sel_hi:[1,0]
	v_max3_f32 v68, v74, v68, v69
	v_max_f32_e32 v64, v70, v71
	v_max_f32_e32 v65, v82, v83
	v_max3_f32 v64, v68, v64, v65
	v_mov_b32_e32 v65, v64
	s_nop 1
	v_permlane16_swap_b32_e32 v65, v64
	s_waitcnt lgkmcnt(0)
	v_max_f32_e32 v65, v65, v65
	v_max_f32_e32 v64, v64, v65
	v_mov_b32_e32 v65, v64
	s_nop 1
	v_permlane32_swap_b32_e32 v65, v64
	s_and_saveexec_b64 s[22:23], s[40:41]
	s_cbranch_execz .LBB0_698
	s_waitcnt lgkmcnt(0)
	v_max_f32_e32 v65, v65, v65
	v_max_f32_e32 v64, v64, v64
	v_max_f32_e32 v64, v64, v65
	ds_write_b32 v223, v64 offset:768
.LBB0_698:
	s_or_b64 exec, exec, s[22:23]
	s_waitcnt vmcnt(0) lgkmcnt(0)
	v_pk_add_f32 v[64:65], v[138:139], v[142:143]
	v_pk_add_f32 v[66:67], v[136:137], v[140:141]
	v_pk_add_f32 v[68:69], v[130:131], v[134:135]
	v_pk_add_f32 v[74:75], v[128:129], v[132:133]
	v_pk_add_f32 v[64:65], v[64:65], v[68:69]
	v_pk_add_f32 v[66:67], v[66:67], v[74:75]
	v_add_f32_e32 v64, v64, v65
	v_add_f32_e32 v66, v66, v67
	v_add_f32_e32 v64, v66, v64
	v_fmamk_f32 v64, v64, 0x3a800000, v244
	v_rsq_f32_e32 v64, v64
	s_nop 0
	v_mul_f32_e32 v64, 0x3db8aa3b, v64
	ds_bpermute_b32 v68, v236, v64
	s_waitcnt lgkmcnt(0)
	v_pk_mul_f32 v[168:169], v[62:63], v[68:69] op_sel_hi:[1,0]
	v_pk_mul_f32 v[172:173], v[60:61], v[68:69] op_sel_hi:[1,0]
	v_max_f32_e32 v61, v168, v169
	v_max_f32_e32 v60, v172, v173
	v_pk_mul_f32 v[62:63], v[58:59], v[68:69] op_sel_hi:[1,0]
	v_pk_mul_f32 v[166:167], v[56:57], v[68:69] op_sel_hi:[1,0]
	v_max3_f32 v60, v60, s6, v61
	v_max_f32_e32 v56, v166, v167
	v_max_f32_e32 v57, v62, v63
	v_max3_f32 v58, v60, v56, v57
	v_pk_mul_f32 v[56:57], v[54:55], v[68:69] op_sel_hi:[1,0]
	v_pk_mul_f32 v[164:165], v[52:53], v[68:69] op_sel_hi:[1,0]
	v_max_f32_e32 v53, v56, v57
	v_max_f32_e32 v52, v164, v165
	v_pk_mul_f32 v[66:67], v[46:47], v[68:69] op_sel_hi:[1,0]
	v_pk_mul_f32 v[54:55], v[44:45], v[68:69] op_sel_hi:[1,0]
	v_max3_f32 v52, v58, v52, v53
	v_max_f32_e32 v44, v54, v55
	v_max_f32_e32 v45, v66, v67
	v_max3_f32 v44, v52, v44, v45
	v_mov_b32_e32 v45, v44
	s_nop 1
	v_permlane16_swap_b32_e32 v45, v44
	s_waitcnt lgkmcnt(0)
	v_max_f32_e32 v45, v45, v45
	v_max_f32_e32 v44, v44, v45
	v_mov_b32_e32 v45, v44
	s_nop 1
	v_permlane32_swap_b32_e32 v45, v44
	s_and_saveexec_b64 s[22:23], s[40:41]
	s_cbranch_execz .LBB0_700
	s_waitcnt lgkmcnt(0)
	v_max_f32_e32 v45, v45, v45
	v_max_f32_e32 v44, v44, v44
	v_max_f32_e32 v44, v44, v45
	ds_write_b32 v224, v44
.LBB0_700:
	s_or_b64 exec, exec, s[22:23]
	v_or_b32_e32 v44, 64, v236
	ds_bpermute_b32 v44, v44, v64
	s_waitcnt lgkmcnt(0)
	v_pk_mul_f32 v[160:161], v[50:51], v[44:45] op_sel_hi:[1,0]
	v_pk_mul_f32 v[162:163], v[48:49], v[44:45] op_sel_hi:[1,0]
	v_pk_mul_f32 v[48:49], v[42:43], v[44:45] op_sel_hi:[1,0]
	v_pk_mul_f32 v[158:159], v[40:41], v[44:45] op_sel_hi:[1,0]
	v_max_f32_e32 v40, v162, v163
	v_max_f32_e32 v41, v160, v161
	v_max3_f32 v40, v40, s6, v41
	v_max_f32_e32 v41, v158, v159
	v_max_f32_e32 v42, v48, v49
	v_max3_f32 v42, v40, v41, v42
	v_pk_mul_f32 v[40:41], v[38:39], v[44:45] op_sel_hi:[1,0]
	v_pk_mul_f32 v[156:157], v[36:37], v[44:45] op_sel_hi:[1,0]
	v_max_f32_e32 v37, v40, v41
	v_max_f32_e32 v36, v156, v157
	v_pk_mul_f32 v[50:51], v[30:31], v[44:45] op_sel_hi:[1,0]
	v_pk_mul_f32 v[38:39], v[28:29], v[44:45] op_sel_hi:[1,0]
	v_max3_f32 v36, v42, v36, v37
	v_max_f32_e32 v28, v38, v39
	v_max_f32_e32 v29, v50, v51
	v_max3_f32 v28, v36, v28, v29
	v_mov_b32_e32 v29, v28
	s_nop 1
	v_permlane16_swap_b32_e32 v29, v28
	s_waitcnt lgkmcnt(0)
	v_max_f32_e32 v29, v29, v29
	v_max_f32_e32 v28, v28, v29
	v_mov_b32_e32 v29, v28
	s_nop 1
	v_permlane32_swap_b32_e32 v29, v28
	s_and_saveexec_b64 s[22:23], s[40:41]
	s_cbranch_execz .LBB0_702
	s_waitcnt lgkmcnt(0)
	v_max_f32_e32 v29, v29, v29
	v_max_f32_e32 v28, v28, v28
	v_max_f32_e32 v28, v28, v29
	ds_write_b32 v223, v28 offset:2304
.LBB0_702:
	s_or_b64 exec, exec, s[22:23]
	v_or_b32_e32 v28, 0x80, v236
	ds_bpermute_b32 v28, v28, v64
	s_waitcnt lgkmcnt(0)
	v_pk_mul_f32 v[140:141], v[34:35], v[28:29] op_sel_hi:[1,0]
	v_pk_mul_f32 v[142:143], v[32:33], v[28:29] op_sel_hi:[1,0]
	v_pk_mul_f32 v[32:33], v[26:27], v[28:29] op_sel_hi:[1,0]
	v_pk_mul_f32 v[138:139], v[24:25], v[28:29] op_sel_hi:[1,0]
	v_max_f32_e32 v24, v142, v143
	v_max_f32_e32 v25, v140, v141
	v_max3_f32 v24, v24, s6, v25
	v_max_f32_e32 v25, v138, v139
	v_max_f32_e32 v26, v32, v33
	v_max3_f32 v26, v24, v25, v26
	v_pk_mul_f32 v[24:25], v[22:23], v[28:29] op_sel_hi:[1,0]
	v_pk_mul_f32 v[136:137], v[20:21], v[28:29] op_sel_hi:[1,0]
	v_max_f32_e32 v21, v24, v25
	v_max_f32_e32 v20, v136, v137
	v_pk_mul_f32 v[34:35], v[14:15], v[28:29] op_sel_hi:[1,0]
	v_pk_mul_f32 v[22:23], v[12:13], v[28:29] op_sel_hi:[1,0]
	v_max3_f32 v20, v26, v20, v21
	v_max_f32_e32 v12, v22, v23
	v_max_f32_e32 v13, v34, v35
	v_max3_f32 v12, v20, v12, v13
	v_mov_b32_e32 v13, v12
	s_nop 1
	v_permlane16_swap_b32_e32 v13, v12
	s_waitcnt lgkmcnt(0)
	v_max_f32_e32 v13, v13, v13
	v_max_f32_e32 v12, v12, v13
	v_mov_b32_e32 v13, v12
	s_nop 1
	v_permlane32_swap_b32_e32 v13, v12
	s_and_saveexec_b64 s[22:23], s[40:41]
	s_cbranch_execz .LBB0_704
	s_waitcnt lgkmcnt(0)
	v_max_f32_e32 v13, v13, v13
	v_max_f32_e32 v12, v12, v12
	v_max_f32_e32 v12, v12, v13
	ds_write_b32 v223, v12 offset:2560
; #define PG8_LAS __attribute__((address_space(3)))
;     __device__ __forceinline__ void operator()(f32x4 (&acc)[2][2][4][2], const Unit& u, int wr, int wc, int fr, int fq) const {
;     ...
;                 mx = fmaxf(mx, __shfl_xor(mx, 16)); mx = fmaxf(mx, __shfl_xor(mx, 32));
;                 if (fq == 0) xch[(ai * HALF + wr * 64 + m * 16 + fr) * 4 + wc] = mx; }
;         asm volatile("s_waitcnt lgkmcnt(0)" ::: "memory"); __builtin_amdgcn_s_barrier(); asm volatile("" ::: "memory");
; #pragma unroll
;         for (int ai = 0; ai < 2; ++ai)
; #pragma unroll
;             for (int m = 0; m < 4; ++m) { const int r = ai * HALF + wr * 64 + m * 16 + fr; const f32x4 m4 = *(const PG8_LAS f32x4*)(xch + r * 4);
;                 const float mx = fmaxf(fmaxf(m4[0], m4[1]), fmaxf(m4[2], m4[3])); float sm_ = 0.f;
; #pragma unroll
;                 for (int bj = 0; bj < 2; ++bj)
; #pragma unroll
;                     for (int n = 0; n < 2; ++n) { f32x4 x = acc[ai][bj][m][n];
; #pragma unroll
;                         for (int j = 0; j < 4; ++j) { x[j] = __builtin_amdgcn_exp2f(x[j] - mx); sm_ += x[j]; }
;                         acc[ai][bj][m][n] = x; }
;                 sm_ += __shfl_xor(sm_, 16); sm_ += __shfl_xor(sm_, 32);
;                 if (fq == 0) xch[1024 + r * 4 + wc] = sm_; }
.LBB0_704:
	s_or_b64 exec, exec, s[22:23]
	v_or_b32_e32 v12, 0xc0, v236
	ds_bpermute_b32 v12, v12, v64
	s_waitcnt lgkmcnt(0)
	v_pk_mul_f32 v[132:133], v[18:19], v[12:13] op_sel_hi:[1,0]
	v_pk_mul_f32 v[134:135], v[16:17], v[12:13] op_sel_hi:[1,0]
	v_pk_mul_f32 v[16:17], v[10:11], v[12:13] op_sel_hi:[1,0]
	v_pk_mul_f32 v[130:131], v[8:9], v[12:13] op_sel_hi:[1,0]
	v_max_f32_e32 v8, v134, v135
	v_max_f32_e32 v9, v132, v133
	v_max3_f32 v8, v8, s6, v9
	v_max_f32_e32 v9, v130, v131
	v_max_f32_e32 v10, v16, v17
	v_max3_f32 v10, v8, v9, v10
	v_pk_mul_f32 v[8:9], v[6:7], v[12:13] op_sel_hi:[1,0]
	v_pk_mul_f32 v[128:129], v[4:5], v[12:13] op_sel_hi:[1,0]
	v_max_f32_e32 v5, v8, v9
	v_max_f32_e32 v4, v128, v129
	v_pk_mul_f32 v[18:19], v[2:3], v[12:13] op_sel_hi:[1,0]
	v_pk_mul_f32 v[6:7], v[0:1], v[12:13] op_sel_hi:[1,0]
	v_max3_f32 v4, v10, v4, v5
	v_max_f32_e32 v0, v6, v7
	v_max_f32_e32 v1, v18, v19
	v_max3_f32 v0, v4, v0, v1
	v_mov_b32_e32 v1, v0
	s_nop 1
	v_permlane16_swap_b32_e32 v1, v0
	s_waitcnt lgkmcnt(0)
	v_max_f32_e32 v1, v1, v1
	v_max_f32_e32 v0, v0, v1
	v_mov_b32_e32 v1, v0
	s_nop 1
	v_permlane32_swap_b32_e32 v1, v0
	s_and_saveexec_b64 s[22:23], s[40:41]
	s_cbranch_execz .LBB0_706
	s_waitcnt lgkmcnt(0)
	v_max_f32_e32 v1, v1, v1
	v_max_f32_e32 v0, v0, v0
	v_max_f32_e32 v0, v0, v1
	ds_write_b32 v223, v0 offset:2816
.LBB0_706:
	s_or_b64 exec, exec, s[22:23]
	s_waitcnt lgkmcnt(0)
	s_barrier
	s_waitcnt lgkmcnt(0)
	ds_read_b128 v[0:3], v225
	s_waitcnt lgkmcnt(0)
	v_max_f32_e32 v3, v3, v3
	v_max_f32_e32 v2, v2, v2
	v_max_f32_e32 v2, v2, v3
	v_max3_f32 v0, v0, v1, v2
	v_sub_f32_e32 v1, v124, v0
	v_sub_f32_e32 v2, v125, v0
	v_exp_f32_e32 v110, v1
	v_exp_f32_e32 v111, v2
	v_sub_f32_e32 v1, v126, v0
	v_exp_f32_e32 v118, v1
	v_sub_f32_e32 v1, v127, v0
	v_exp_f32_e32 v119, v1
	v_sub_f32_e32 v2, v180, v0
	v_add_f32_e32 v1, 0, v110
	v_exp_f32_e32 v116, v2
	v_sub_f32_e32 v2, v181, v0
	v_add_f32_e32 v1, v111, v1
	v_exp_f32_e32 v117, v2
	v_sub_f32_e32 v2, v122, v0
	v_add_f32_e32 v1, v118, v1
	v_exp_f32_e32 v124, v2
	v_sub_f32_e32 v2, v123, v0
	v_add_f32_e32 v1, v119, v1
	v_exp_f32_e32 v125, v2
	v_sub_f32_e32 v2, v182, v0
	v_add_f32_e32 v1, v116, v1
	v_exp_f32_e32 v108, v2
	v_sub_f32_e32 v2, v183, v0
	v_add_f32_e32 v1, v117, v1
	v_exp_f32_e32 v109, v2
	v_sub_f32_e32 v2, v120, v0
	v_add_f32_e32 v1, v124, v1
	v_exp_f32_e32 v122, v2
	v_sub_f32_e32 v2, v121, v0
	v_add_f32_e32 v1, v125, v1
	v_exp_f32_e32 v123, v2
	v_sub_f32_e32 v2, v112, v0
	v_add_f32_e32 v1, v108, v1
	v_exp_f32_e32 v120, v2
	v_sub_f32_e32 v2, v113, v0
	v_add_f32_e32 v1, v109, v1
	v_exp_f32_e32 v121, v2
	v_sub_f32_e32 v2, v114, v0
	v_add_f32_e32 v1, v122, v1
	v_exp_f32_e32 v126, v2
	v_sub_f32_e32 v0, v115, v0
	v_add_f32_e32 v1, v123, v1
	v_exp_f32_e32 v127, v0
	v_add_f32_e32 v0, v120, v1
	v_add_f32_e32 v0, v121, v0
	v_add_f32_e32 v0, v126, v0
	v_add_f32_e32 v0, v127, v0
	v_mov_b32_e32 v1, v0
	s_nop 1
	v_permlane16_swap_b32_e32 v1, v0
	s_waitcnt lgkmcnt(0)
	v_add_f32_e32 v0, v0, v1
	v_mov_b32_e32 v1, v0
	s_nop 1
	v_permlane32_swap_b32_e32 v1, v0
	s_and_saveexec_b64 s[22:23], s[40:41]
	s_cbranch_execz .LBB0_708
	s_waitcnt lgkmcnt(0)
	v_add_f32_e32 v0, v0, v1
	ds_write_b32 v226, v0 offset:4096
.LBB0_708:
	s_or_b64 exec, exec, s[22:23]
	s_waitcnt lgkmcnt(0)
	ds_read_b128 v[0:3], v225 offset:256
	s_waitcnt lgkmcnt(0)
	v_max_f32_e32 v3, v3, v3
	v_max_f32_e32 v2, v2, v2
	v_max_f32_e32 v2, v2, v3
	v_max3_f32 v0, v0, v1, v2
	v_sub_f32_e32 v1, v208, v0
	v_sub_f32_e32 v2, v209, v0
	v_exp_f32_e32 v94, v1
	v_sub_f32_e32 v3, v206, v0
	v_exp_f32_e32 v95, v2
	v_sub_f32_e32 v4, v207, v0
	v_exp_f32_e32 v106, v3
	v_exp_f32_e32 v107, v4
	v_sub_f32_e32 v2, v204, v0
	v_add_f32_e32 v1, 0, v94
	v_exp_f32_e32 v100, v2
	v_sub_f32_e32 v2, v205, v0
	v_add_f32_e32 v1, v95, v1
	v_exp_f32_e32 v101, v2
	v_sub_f32_e32 v2, v200, v0
	v_add_f32_e32 v1, v106, v1
	v_exp_f32_e32 v112, v2
	v_sub_f32_e32 v2, v201, v0
	v_add_f32_e32 v1, v107, v1
	v_exp_f32_e32 v113, v2
	v_sub_f32_e32 v2, v202, v0
	v_add_f32_e32 v1, v100, v1
	v_exp_f32_e32 v92, v2
	v_sub_f32_e32 v2, v203, v0
	v_add_f32_e32 v1, v101, v1
	v_exp_f32_e32 v93, v2
	v_sub_f32_e32 v2, v104, v0
	v_add_f32_e32 v1, v112, v1
	v_exp_f32_e32 v104, v2
	v_sub_f32_e32 v2, v105, v0
	v_add_f32_e32 v1, v113, v1
	v_exp_f32_e32 v105, v2
	v_sub_f32_e32 v2, v102, v0
	v_add_f32_e32 v1, v92, v1
	v_exp_f32_e32 v102, v2
	v_sub_f32_e32 v2, v103, v0
	v_add_f32_e32 v1, v93, v1
	v_exp_f32_e32 v103, v2
	v_sub_f32_e32 v2, v198, v0
	v_add_f32_e32 v1, v104, v1
	v_exp_f32_e32 v114, v2
	v_sub_f32_e32 v0, v199, v0
	v_add_f32_e32 v1, v105, v1
	v_exp_f32_e32 v115, v0
	v_add_f32_e32 v0, v102, v1
	v_add_f32_e32 v0, v103, v0
	v_add_f32_e32 v0, v114, v0
	v_add_f32_e32 v0, v115, v0
	v_mov_b32_e32 v1, v0
	s_nop 1
	v_permlane16_swap_b32_e32 v1, v0
	s_waitcnt lgkmcnt(0)
	v_add_f32_e32 v0, v0, v1
	v_mov_b32_e32 v1, v0
	s_nop 1
	v_permlane32_swap_b32_e32 v1, v0
	s_and_saveexec_b64 s[22:23], s[40:41]
	s_cbranch_execz .LBB0_710
	s_waitcnt lgkmcnt(0)
	v_add_f32_e32 v0, v0, v1
	ds_write_b32 v226, v0 offset:4352
; #define PG8_LAS __attribute__((address_space(3)))
;     __device__ __forceinline__ void operator()(f32x4 (&acc)[2][2][4][2], const Unit& u, int wr, int wc, int fr, int fq) const {
;     ...
;             for (int m = 0; m < 4; ++m) { const int r = ai * HALF + wr * 64 + m * 16 + fr; const f32x4 m4 = *(const PG8_LAS f32x4*)(xch + r * 4);
;                 const float mx = fmaxf(fmaxf(m4[0], m4[1]), fmaxf(m4[2], m4[3])); float sm_ = 0.f;
; #pragma unroll
;                 for (int bj = 0; bj < 2; ++bj)
; #pragma unroll
;                     for (int n = 0; n < 2; ++n) { f32x4 x = acc[ai][bj][m][n];
; #pragma unroll
;                         for (int j = 0; j < 4; ++j) { x[j] = __builtin_amdgcn_exp2f(x[j] - mx); sm_ += x[j]; }
;                         acc[ai][bj][m][n] = x; }
;                 sm_ += __shfl_xor(sm_, 16); sm_ += __shfl_xor(sm_, 32);
;                 if (fq == 0) xch[1024 + r * 4 + wc] = sm_; }
.LBB0_710:
	s_or_b64 exec, exec, s[22:23]
	s_waitcnt lgkmcnt(0)
	ds_read_b128 v[0:3], v225 offset:512
	s_waitcnt lgkmcnt(0)
	v_max_f32_e32 v3, v3, v3
	v_max_f32_e32 v2, v2, v2
	v_max_f32_e32 v2, v2, v3
	v_max3_f32 v0, v0, v1, v2
	v_sub_f32_e32 v1, v190, v0
	v_sub_f32_e32 v2, v191, v0
	v_exp_f32_e32 v78, v1
	v_sub_f32_e32 v3, v188, v0
	v_exp_f32_e32 v79, v2
	v_sub_f32_e32 v4, v189, v0
	v_exp_f32_e32 v90, v3
	v_exp_f32_e32 v91, v4
	v_sub_f32_e32 v2, v186, v0
	v_add_f32_e32 v1, 0, v78
	v_exp_f32_e32 v84, v2
	v_sub_f32_e32 v2, v187, v0
	v_add_f32_e32 v1, v79, v1
	v_exp_f32_e32 v85, v2
	v_sub_f32_e32 v2, v96, v0
	v_add_f32_e32 v1, v90, v1
	v_exp_f32_e32 v96, v2
	v_sub_f32_e32 v2, v97, v0
	v_add_f32_e32 v1, v91, v1
	v_exp_f32_e32 v97, v2
	v_sub_f32_e32 v2, v184, v0
	v_add_f32_e32 v1, v84, v1
	v_exp_f32_e32 v76, v2
	v_sub_f32_e32 v2, v185, v0
	v_add_f32_e32 v1, v85, v1
	v_exp_f32_e32 v77, v2
	v_sub_f32_e32 v2, v88, v0
	v_add_f32_e32 v1, v96, v1
	v_exp_f32_e32 v88, v2
	v_sub_f32_e32 v2, v89, v0
	v_add_f32_e32 v1, v97, v1
	v_exp_f32_e32 v89, v2
	v_sub_f32_e32 v2, v86, v0
	v_add_f32_e32 v1, v76, v1
	v_exp_f32_e32 v86, v2
	v_sub_f32_e32 v2, v87, v0
	v_add_f32_e32 v1, v77, v1
	v_exp_f32_e32 v87, v2
	v_sub_f32_e32 v2, v98, v0
	v_add_f32_e32 v1, v88, v1
	v_exp_f32_e32 v98, v2
	v_sub_f32_e32 v0, v99, v0
	v_add_f32_e32 v1, v89, v1
	v_exp_f32_e32 v99, v0
	v_add_f32_e32 v0, v86, v1
	v_add_f32_e32 v0, v87, v0
	v_add_f32_e32 v0, v98, v0
	v_add_f32_e32 v0, v99, v0
	v_mov_b32_e32 v1, v0
	s_nop 1
	v_permlane16_swap_b32_e32 v1, v0
	s_waitcnt lgkmcnt(0)
	v_add_f32_e32 v0, v0, v1
	v_mov_b32_e32 v1, v0
	s_nop 1
	v_permlane32_swap_b32_e32 v1, v0
	s_and_saveexec_b64 s[22:23], s[40:41]
	s_cbranch_execz .LBB0_712
	s_waitcnt lgkmcnt(0)
	v_add_f32_e32 v0, v0, v1
	ds_write_b32 v226, v0 offset:4608
.LBB0_712:
	s_or_b64 exec, exec, s[22:23]
	s_waitcnt lgkmcnt(0)
	ds_read_b128 v[0:3], v225 offset:768
	s_waitcnt lgkmcnt(0)
	v_max_f32_e32 v3, v3, v3
	v_max_f32_e32 v2, v2, v2
	v_max_f32_e32 v2, v2, v3
	v_max3_f32 v0, v0, v1, v2
	v_sub_f32_e32 v1, v178, v0
	v_sub_f32_e32 v2, v179, v0
	v_exp_f32_e32 v64, v1
	v_sub_f32_e32 v3, v176, v0
	v_exp_f32_e32 v65, v2
	v_sub_f32_e32 v4, v177, v0
	v_exp_f32_e32 v74, v3
	v_exp_f32_e32 v75, v4
	v_sub_f32_e32 v2, v174, v0
	v_add_f32_e32 v1, 0, v64
	v_exp_f32_e32 v68, v2
	v_sub_f32_e32 v2, v175, v0
	v_add_f32_e32 v1, v65, v1
	v_exp_f32_e32 v69, v2
	v_sub_f32_e32 v2, v80, v0
	v_add_f32_e32 v1, v74, v1
	v_exp_f32_e32 v80, v2
	v_sub_f32_e32 v2, v81, v0
	v_add_f32_e32 v1, v75, v1
	v_exp_f32_e32 v81, v2
	v_sub_f32_e32 v2, v170, v0
	v_add_f32_e32 v1, v68, v1
	v_exp_f32_e32 v60, v2
	v_sub_f32_e32 v2, v171, v0
	v_add_f32_e32 v1, v69, v1
	v_exp_f32_e32 v61, v2
	v_sub_f32_e32 v2, v72, v0
	v_add_f32_e32 v1, v80, v1
	v_exp_f32_e32 v72, v2
	v_sub_f32_e32 v2, v73, v0
	v_add_f32_e32 v1, v81, v1
	v_exp_f32_e32 v73, v2
	v_sub_f32_e32 v2, v70, v0
	v_add_f32_e32 v1, v60, v1
	v_exp_f32_e32 v70, v2
	v_sub_f32_e32 v2, v71, v0
	v_add_f32_e32 v1, v61, v1
	v_exp_f32_e32 v71, v2
	v_sub_f32_e32 v2, v82, v0
	v_add_f32_e32 v1, v72, v1
	v_exp_f32_e32 v82, v2
	v_sub_f32_e32 v0, v83, v0
	v_add_f32_e32 v1, v73, v1
	v_exp_f32_e32 v83, v0
	v_add_f32_e32 v0, v70, v1
	v_add_f32_e32 v0, v71, v0
	v_add_f32_e32 v0, v82, v0
	v_add_f32_e32 v0, v83, v0
	v_mov_b32_e32 v1, v0
	s_nop 1
	v_permlane16_swap_b32_e32 v1, v0
	s_waitcnt lgkmcnt(0)
	v_add_f32_e32 v0, v0, v1
	v_mov_b32_e32 v1, v0
	s_nop 1
	v_permlane32_swap_b32_e32 v1, v0
	s_and_saveexec_b64 s[22:23], s[40:41]
	s_cbranch_execz .LBB0_714
	s_waitcnt lgkmcnt(0)
	v_add_f32_e32 v0, v0, v1
	ds_write_b32 v226, v0 offset:4864
.LBB0_714:
	s_or_b64 exec, exec, s[22:23]
	s_waitcnt lgkmcnt(0)
	ds_read_b128 v[0:3], v225 offset:2048
	s_waitcnt lgkmcnt(0)
	v_max_f32_e32 v3, v3, v3
	v_max_f32_e32 v2, v2, v2
	v_max_f32_e32 v2, v2, v3
	v_max3_f32 v0, v0, v1, v2
	v_sub_f32_e32 v1, v172, v0
	v_sub_f32_e32 v2, v173, v0
	v_exp_f32_e32 v46, v1
	v_sub_f32_e32 v3, v168, v0
	v_exp_f32_e32 v47, v2
	v_sub_f32_e32 v4, v169, v0
	v_exp_f32_e32 v58, v3
	v_exp_f32_e32 v59, v4
	v_sub_f32_e32 v2, v166, v0
	v_add_f32_e32 v1, 0, v46
	v_exp_f32_e32 v52, v2
	v_sub_f32_e32 v2, v167, v0
	v_add_f32_e32 v1, v47, v1
	v_exp_f32_e32 v53, v2
	v_sub_f32_e32 v2, v62, v0
	v_add_f32_e32 v1, v58, v1
	v_exp_f32_e32 v62, v2
	v_sub_f32_e32 v2, v63, v0
	v_add_f32_e32 v1, v59, v1
	v_exp_f32_e32 v63, v2
	v_sub_f32_e32 v2, v164, v0
	v_add_f32_e32 v1, v52, v1
	v_exp_f32_e32 v44, v2
	v_sub_f32_e32 v2, v165, v0
	v_add_f32_e32 v1, v53, v1
	v_exp_f32_e32 v45, v2
	v_sub_f32_e32 v2, v56, v0
	v_add_f32_e32 v1, v62, v1
	v_exp_f32_e32 v56, v2
	v_sub_f32_e32 v2, v57, v0
	v_add_f32_e32 v1, v63, v1
	v_exp_f32_e32 v57, v2
	v_sub_f32_e32 v2, v54, v0
	v_add_f32_e32 v1, v44, v1
	v_exp_f32_e32 v54, v2
	v_sub_f32_e32 v2, v55, v0
	v_add_f32_e32 v1, v45, v1
	v_exp_f32_e32 v55, v2
	v_sub_f32_e32 v2, v66, v0
	v_add_f32_e32 v1, v56, v1
	v_exp_f32_e32 v66, v2
	v_sub_f32_e32 v0, v67, v0
	v_add_f32_e32 v1, v57, v1
	v_exp_f32_e32 v67, v0
	v_add_f32_e32 v0, v54, v1
	v_add_f32_e32 v0, v55, v0
	v_add_f32_e32 v0, v66, v0
	v_add_f32_e32 v0, v67, v0
	v_mov_b32_e32 v1, v0
	s_nop 1
	v_permlane16_swap_b32_e32 v1, v0
	s_waitcnt lgkmcnt(0)
	v_add_f32_e32 v0, v0, v1
	v_mov_b32_e32 v1, v0
	s_nop 1
	v_permlane32_swap_b32_e32 v1, v0
	s_and_saveexec_b64 s[22:23], s[40:41]
	s_cbranch_execz .LBB0_716
	s_waitcnt lgkmcnt(0)
	v_add_f32_e32 v0, v0, v1
	ds_write_b32 v226, v0 offset:6144
; #define PG8_LAS __attribute__((address_space(3)))
;     __device__ __forceinline__ void operator()(f32x4 (&acc)[2][2][4][2], const Unit& u, int wr, int wc, int fr, int fq) const {
;     ...
;             for (int m = 0; m < 4; ++m) { const int r = ai * HALF + wr * 64 + m * 16 + fr; const f32x4 m4 = *(const PG8_LAS f32x4*)(xch + r * 4);
;                 const float mx = fmaxf(fmaxf(m4[0], m4[1]), fmaxf(m4[2], m4[3])); float sm_ = 0.f;
; #pragma unroll
;                 for (int bj = 0; bj < 2; ++bj)
; #pragma unroll
;                     for (int n = 0; n < 2; ++n) { f32x4 x = acc[ai][bj][m][n];
; #pragma unroll
;                         for (int j = 0; j < 4; ++j) { x[j] = __builtin_amdgcn_exp2f(x[j] - mx); sm_ += x[j]; }
;                         acc[ai][bj][m][n] = x; }
;                 sm_ += __shfl_xor(sm_, 16); sm_ += __shfl_xor(sm_, 32);
;                 if (fq == 0) xch[1024 + r * 4 + wc] = sm_; }
.LBB0_716:
	s_or_b64 exec, exec, s[22:23]
	s_waitcnt lgkmcnt(0)
	ds_read_b128 v[0:3], v225 offset:2304
	s_waitcnt lgkmcnt(0)
	v_max_f32_e32 v3, v3, v3
	v_max_f32_e32 v2, v2, v2
	v_max_f32_e32 v2, v2, v3
	v_max3_f32 v0, v0, v1, v2
	v_sub_f32_e32 v1, v162, v0
	v_sub_f32_e32 v2, v163, v0
	v_exp_f32_e32 v30, v1
	v_sub_f32_e32 v3, v160, v0
	v_exp_f32_e32 v31, v2
	v_sub_f32_e32 v4, v161, v0
	v_exp_f32_e32 v42, v3
	v_exp_f32_e32 v43, v4
	v_sub_f32_e32 v2, v158, v0
	v_add_f32_e32 v1, 0, v30
	v_exp_f32_e32 v36, v2
	v_sub_f32_e32 v2, v159, v0
	v_add_f32_e32 v1, v31, v1
	v_exp_f32_e32 v37, v2
	v_sub_f32_e32 v2, v48, v0
	v_add_f32_e32 v1, v42, v1
	v_exp_f32_e32 v48, v2
	v_sub_f32_e32 v2, v49, v0
	v_add_f32_e32 v1, v43, v1
	v_exp_f32_e32 v49, v2
	v_sub_f32_e32 v2, v156, v0
	v_add_f32_e32 v1, v36, v1
	v_exp_f32_e32 v28, v2
	v_sub_f32_e32 v2, v157, v0
	v_add_f32_e32 v1, v37, v1
	v_exp_f32_e32 v29, v2
	v_sub_f32_e32 v2, v40, v0
	v_add_f32_e32 v1, v48, v1
	v_exp_f32_e32 v40, v2
	v_sub_f32_e32 v2, v41, v0
	v_add_f32_e32 v1, v49, v1
	v_exp_f32_e32 v41, v2
	v_sub_f32_e32 v2, v38, v0
	v_add_f32_e32 v1, v28, v1
	v_exp_f32_e32 v38, v2
	v_sub_f32_e32 v2, v39, v0
	v_add_f32_e32 v1, v29, v1
	v_exp_f32_e32 v39, v2
	v_sub_f32_e32 v2, v50, v0
	v_add_f32_e32 v1, v40, v1
	v_exp_f32_e32 v50, v2
	v_sub_f32_e32 v0, v51, v0
	v_add_f32_e32 v1, v41, v1
	v_exp_f32_e32 v51, v0
	v_add_f32_e32 v0, v38, v1
	v_add_f32_e32 v0, v39, v0
	v_add_f32_e32 v0, v50, v0
	v_add_f32_e32 v0, v51, v0
	v_mov_b32_e32 v1, v0
	s_nop 1
	v_permlane16_swap_b32_e32 v1, v0
	s_waitcnt lgkmcnt(0)
	v_add_f32_e32 v0, v0, v1
	v_mov_b32_e32 v1, v0
	s_nop 1
	v_permlane32_swap_b32_e32 v1, v0
	s_and_saveexec_b64 s[22:23], s[40:41]
	s_cbranch_execz .LBB0_718
	s_waitcnt lgkmcnt(0)
	v_add_f32_e32 v0, v0, v1
	ds_write_b32 v226, v0 offset:6400
.LBB0_718:
	s_or_b64 exec, exec, s[22:23]
	s_waitcnt lgkmcnt(0)
	ds_read_b128 v[0:3], v225 offset:2560
	s_waitcnt lgkmcnt(0)
	v_max_f32_e32 v3, v3, v3
	v_max_f32_e32 v2, v2, v2
	v_max_f32_e32 v2, v2, v3
	v_max3_f32 v0, v0, v1, v2
	v_sub_f32_e32 v1, v142, v0
	v_sub_f32_e32 v2, v143, v0
	v_exp_f32_e32 v14, v1
	v_sub_f32_e32 v3, v140, v0
	v_exp_f32_e32 v15, v2
	v_sub_f32_e32 v4, v141, v0
	v_exp_f32_e32 v26, v3
	v_exp_f32_e32 v27, v4
	v_sub_f32_e32 v2, v138, v0
	v_add_f32_e32 v1, 0, v14
	v_exp_f32_e32 v20, v2
	v_sub_f32_e32 v2, v139, v0
	v_add_f32_e32 v1, v15, v1
	v_exp_f32_e32 v21, v2
	v_sub_f32_e32 v2, v32, v0
	v_add_f32_e32 v1, v26, v1
	v_exp_f32_e32 v32, v2
	v_sub_f32_e32 v2, v33, v0
	v_add_f32_e32 v1, v27, v1
	v_exp_f32_e32 v33, v2
	v_sub_f32_e32 v2, v136, v0
	v_add_f32_e32 v1, v20, v1
	v_exp_f32_e32 v12, v2
	v_sub_f32_e32 v2, v137, v0
	v_add_f32_e32 v1, v21, v1
	v_exp_f32_e32 v13, v2
	v_sub_f32_e32 v2, v24, v0
	v_add_f32_e32 v1, v32, v1
	v_exp_f32_e32 v24, v2
	v_sub_f32_e32 v2, v25, v0
	v_add_f32_e32 v1, v33, v1
	v_exp_f32_e32 v25, v2
	v_sub_f32_e32 v2, v22, v0
	v_add_f32_e32 v1, v12, v1
	v_exp_f32_e32 v22, v2
	v_sub_f32_e32 v2, v23, v0
	v_add_f32_e32 v1, v13, v1
	v_exp_f32_e32 v23, v2
	v_sub_f32_e32 v2, v34, v0
	v_add_f32_e32 v1, v24, v1
	v_exp_f32_e32 v34, v2
	v_sub_f32_e32 v0, v35, v0
	v_add_f32_e32 v1, v25, v1
	v_exp_f32_e32 v35, v0
	v_add_f32_e32 v0, v22, v1
	v_add_f32_e32 v0, v23, v0
	v_add_f32_e32 v0, v34, v0
	v_add_f32_e32 v0, v35, v0
	v_mov_b32_e32 v1, v0
	s_nop 1
	v_permlane16_swap_b32_e32 v1, v0
	s_waitcnt lgkmcnt(0)
	v_add_f32_e32 v0, v0, v1
	v_mov_b32_e32 v1, v0
	s_nop 1
	v_permlane32_swap_b32_e32 v1, v0
	s_and_saveexec_b64 s[22:23], s[40:41]
	s_cbranch_execz .LBB0_720
	s_waitcnt lgkmcnt(0)
	v_add_f32_e32 v0, v0, v1
	ds_write_b32 v226, v0 offset:6656
.LBB0_720:
	s_or_b64 exec, exec, s[22:23]
	s_waitcnt lgkmcnt(0)
	ds_read_b128 v[0:3], v225 offset:2816
	s_waitcnt lgkmcnt(0)
	v_max_f32_e32 v3, v3, v3
	v_max_f32_e32 v2, v2, v2
	v_max_f32_e32 v2, v2, v3
	v_max3_f32 v136, v0, v1, v2
	v_sub_f32_e32 v0, v134, v136
	v_sub_f32_e32 v1, v135, v136
	v_exp_f32_e32 v2, v0
	v_sub_f32_e32 v4, v132, v136
	v_exp_f32_e32 v3, v1
	v_sub_f32_e32 v5, v133, v136
	v_exp_f32_e32 v10, v4
	v_exp_f32_e32 v11, v5
	v_sub_f32_e32 v1, v130, v136
	v_add_f32_e32 v0, 0, v2
	v_exp_f32_e32 v4, v1
	v_sub_f32_e32 v1, v131, v136
	v_add_f32_e32 v0, v3, v0
	v_exp_f32_e32 v5, v1
	v_sub_f32_e32 v1, v16, v136
	v_add_f32_e32 v0, v10, v0
	v_exp_f32_e32 v16, v1
	v_sub_f32_e32 v1, v17, v136
	v_add_f32_e32 v0, v11, v0
	v_exp_f32_e32 v17, v1
	v_add_f32_e32 v0, v4, v0
	v_add_f32_e32 v0, v5, v0
	v_add_f32_e32 v0, v16, v0
	v_add_f32_e32 v130, v17, v0
	v_sub_f32_e32 v0, v128, v136
	v_exp_f32_e32 v0, v0
	v_sub_f32_e32 v1, v129, v136
	v_exp_f32_e32 v1, v1
	v_sub_f32_e32 v8, v8, v136
	v_exp_f32_e32 v8, v8
	v_sub_f32_e32 v9, v9, v136
	v_exp_f32_e32 v9, v9
	v_sub_f32_e32 v6, v6, v136
	v_add_f32_e32 v128, v0, v130
	v_exp_f32_e32 v6, v6
	v_sub_f32_e32 v7, v7, v136
	v_add_f32_e32 v128, v1, v128
	v_exp_f32_e32 v7, v7
	v_sub_f32_e32 v18, v18, v136
	v_add_f32_e32 v128, v8, v128
	v_exp_f32_e32 v18, v18
	v_sub_f32_e32 v19, v19, v136
	v_add_f32_e32 v128, v9, v128
	v_exp_f32_e32 v19, v19
	v_add_f32_e32 v128, v6, v128
	v_add_f32_e32 v128, v7, v128
	v_add_f32_e32 v128, v18, v128
	v_add_f32_e32 v128, v19, v128
	v_mov_b32_e32 v129, v128
	s_nop 1
	v_permlane16_swap_b32_e32 v129, v128
	s_waitcnt lgkmcnt(0)
	v_add_f32_e32 v128, v128, v129
	v_mov_b32_e32 v129, v128
	s_nop 1
	v_permlane32_swap_b32_e32 v129, v128
	s_and_saveexec_b64 s[22:23], s[40:41]
	s_cbranch_execz .LBB0_722
	s_waitcnt lgkmcnt(0)
	v_add_f32_e32 v128, v128, v129
	ds_write_b32 v226, v128 offset:6912
